# in-proj: first 8 LDS-DMA loads of the next tile issued before the current tile's epilogue (prologue latency under the epilogue)
# speedup vs baseline: 1.0160x; 1.0068x over previous
; DI void phase_inproj(const Params& p, int layer, char* lds) {
;     ...
;   int tid_ = threadIdx.x; asm volatile("" : "+v"(tid_)); const int tid = tid_, lane = tid & 63, w = tid >> 6, l32 = lane & 31, hh = lane >> 5, wm = w & 1, wn = w >> 1;
;   constexpr int NTN = 11, NRB = T / 256, NTILES = NRB * NTN;
;   const float SC_DQ = 0.17677669529663687f * LOG2E, SC_SQ = 0.125f * LOG2E;
;   const bool xcd_ok = (gridDim.x % 8) == 0;
;   const int xj = xcd_ok ? (int)(blockIdx.x & 7) : 0, nbl = xcd_ok ? (int)(gridDim.x >> 3) : (int)gridDim.x;
;   const int bl = xcd_ok ? (int)(blockIdx.x >> 3) : (int)blockIdx.x, per_x = xcd_ok ? NTILES / 8 : NTILES;
;   for (int u = bl; u < per_x; u += nbl) {
.LBB0_79:
	v_readlane_b32 s4, v255, 22
	v_readlane_b32 s5, v255, 23
	s_mov_b32 s81, s5
	v_readlane_b32 s4, v254, 33
	v_readlane_b32 s5, v254, 34
	v_mov_b32_e32 v0, v184
	s_andn2_b64 vcc, exec, s[4:5]
	s_cbranch_vccnz .LBB0_152
	v_lshrrev_b32_e32 v1, 1, v0
	s_mul_i32 s5, s80, 0x570000
	v_and_b32_e32 v131, 0x60, v1
	v_ashrrev_i32_e32 v1, 2, v0
	s_mul_hi_u32 s4, s80, 0x570000
	s_add_u32 s20, s34, s5
	v_and_b32_e32 v130, 15, v0
	v_and_b32_e32 v1, 0xffffffc0, v1
	v_lshrrev_b32_e32 v0, 2, v0
	s_addc_u32 s21, s35, s4
	v_and_or_b32 v144, v0, 12, v1
	v_readlane_b32 s23, v254, 53
	s_mov_b32 s32, 0
	s_branch .LBB0_82

; #define G8_WV(n) asm volatile("s_waitcnt vmcnt(" #n ")" ::: "memory")
; #define G8_BAR __builtin_amdgcn_s_barrier()
; DI void gemm8p(const u16* __restrict__ A, const u16* __restrict__ Bt, int brow, int bcol, f32x4 (&acc)[2][2][4][2]) {
;     ...
;   int tid8 = threadIdx.x; asm volatile("" : "+v"(tid8));
;   const int wid = tid8 >> 6, lane = tid8 & 63, wr = wid >> 2, wc = wid & 3, fr = lane & 15, fq = lane >> 4;
;   int soff0, soff1;
;   { int r_, c_; g8_stage_rc(tid8 * 16, r_, c_); soff0 = r_ * K + c_; g8_stage_rc(tid8 * 16 + 8192, r_, c_); soff1 = r_ * K + c_; }
;   bf16x8 At[4][2], B0[2][2], B1[2][2];
;   constexpr int nt = K / BK;
;   __syncthreads();
;   G8_STAGE(G8_SB(0, 0), Bt, bcol, 0); G8_STAGE(G8_SA(0, 0), A, brow, 0);
;   G8_STAGE(G8_SB(0, 1), Bt, bcol + HALF, 0); G8_STAGE(G8_SA(0, 1), A, brow + HALF, 0);
;   if (wr == 1) G8_BAR;
;   G8_WV(4); G8_BAR;
;   G8_STAGE(G8_SB(1, 0), Bt, bcol, 1); G8_STAGE(G8_SA(1, 0), A, brow, 1); G8_STAGE(G8_SB(1, 1), Bt, bcol + HALF, 1);
;   G8_WV(6); G8_BAR;
; DI void phase_inproj(const Params& p, int layer, char* lds) {
;     ...
;     const int lr = u / NTN, nt = u % NTN;
;     const int mt = xcd_ok ? lr * 8 + xj : lr, m0 = mt * 256, n0 = nt * 256;
;     const int nvalid = (DIN - n0) < 256 ? (DIN - n0) : 256;
.LBB0_82:
	s_cmp_lg_u32 s32, 0
	s_cselect_b64 vcc, -1, 0
	v_mov_b32_e32 v4, v184
	s_mul_hi_i32 s4, s23, 0x2e8ba2e9
	v_ashrrev_i32_e32 v0, 31, v4
	v_lshrrev_b32_e32 v0, 26, v0
	v_add_u32_e32 v0, v4, v0
	v_ashrrev_i32_e32 v14, 6, v0
	v_bfe_i32 v0, v4, 27, 1
	v_lshlrev_b32_e32 v22, 4, v4
	v_lshrrev_b32_e32 v0, 22, v0
	v_add_u32_e32 v0, v22, v0
	v_and_b32_e32 v0, 0xfffffc00, v0
	v_sub_u32_e32 v0, v22, v0
	v_lshrrev_b32_e32 v1, 4, v0
	v_bitop3_b32 v0, v1, v0, 32 bitop3:0x6c
	v_ashrrev_i32_e32 v2, 31, v0
	v_lshrrev_b32_e32 v2, 26, v2
	v_lshlrev_b32_e32 v1, 3, v14
	v_add_u32_e32 v2, v0, v2
	v_and_b32_e32 v1, 0x3ffff0, v1
	v_ashrrev_i32_e32 v15, 6, v2
	v_lshlrev_b32_e32 v3, 5, v14
	v_and_b32_e32 v2, 0xc0, v2
	v_add_u32_e32 v1, v15, v1
	v_and_b32_e32 v16, 32, v3
	v_sub_u32_e32 v0, v0, v2
	v_ashrrev_i16_sdwa v17, v185, sext(v0) dst_sel:DWORD dst_unused:UNUSED_PAD src0_sel:DWORD src1_sel:BYTE_0
	v_lshl_or_b32 v0, v1, 10, v16
	v_add_u32_e32 v1, 0x2000, v22
	v_ashrrev_i32_e32 v2, 31, v1
	v_lshrrev_b32_e32 v2, 22, v2
	v_add_u32_e32 v2, v1, v2
	s_lshr_b32 s5, s4, 31
	s_ashr_i32 s4, s4, 1
	v_ashrrev_i32_e32 v18, 10, v2
	s_add_i32 s6, s4, s5
	v_mul_i32_i24_e32 v2, 0x400, v18
	s_lshl_b32 s4, s6, 3
	v_sub_u32_e32 v1, v1, v2
	s_or_b32 s7, s4, s28
	v_readlane_b32 s4, v254, 30
	v_lshrrev_b32_e32 v2, 4, v1
	v_readlane_b32 s5, v254, 31
	v_bitop3_b32 v1, v2, v1, 32 bitop3:0x6c
	s_and_b64 s[4:5], s[4:5], exec
	v_ashrrev_i32_e32 v3, 31, v1
	s_cselect_b32 s24, s7, s6
	s_mul_i32 s6, s6, 11
	v_lshrrev_b32_e32 v3, 26, v3
	s_sub_i32 s5, s23, s6
	v_lshlrev_b32_e32 v2, 3, v18
	v_add_u32_e32 v3, v1, v3
	s_lshl_b32 s6, s5, 8
	v_and_b32_e32 v2, 0x3ffff0, v2
	v_ashrrev_i32_e32 v19, 6, v3
	v_lshlrev_b32_e32 v6, 5, v18
	v_and_b32_e32 v3, 0xc0, v3
	v_add_u32_e32 v2, v19, v2
	v_and_b32_e32 v20, 32, v6
	v_sub_u32_e32 v1, v1, v3
	s_ashr_i32 s7, s6, 31
	s_lshl_b32 s4, s24, 8
	v_add_u32_sdwa v0, v0, sext(v17) dst_sel:DWORD dst_unused:UNUSED_PAD src0_sel:DWORD src1_sel:WORD_0
	v_ashrrev_i16_sdwa v21, v185, sext(v1) dst_sel:DWORD dst_unused:UNUSED_PAD src0_sel:DWORD src1_sel:BYTE_0
	v_lshl_or_b32 v1, v2, 10, v20
	s_lshl_b64 s[8:9], s[6:7], 11
	v_readlane_b32 s5, v255, 7
	v_add_u32_sdwa v2, v1, sext(v21) dst_sel:DWORD dst_unused:UNUSED_PAD src0_sel:DWORD src1_sel:WORD_0
	s_add_u32 s10, s20, s8
	v_ashrrev_i32_e32 v1, 31, v0
	v_add_u32_e32 v149, s5, v22
	s_addc_u32 s11, s21, s9
	v_lshlrev_b64 v[24:25], 1, v[0:1]
	v_readfirstlane_b32 s5, v149
	v_add_u32_e32 v150, 0x2000, v149
	v_lshl_add_u64 v[0:1], s[10:11], 0, v[24:25]
	s_mov_b32 m0, s5
	v_ashrrev_i32_e32 v3, 31, v2
	v_readfirstlane_b32 s5, v150
	s_barrier
	s_cbranch_vccnz .Lipf_s0
	global_load_lds_dwordx4 v[0:1], off
.Lipf_s0:
	v_lshlrev_b64 v[26:27], 1, v[2:3]
	s_mov_b32 m0, s5
	s_ashr_i32 s5, s4, 31
	v_lshl_add_u64 v[2:3], s[10:11], 0, v[26:27]
	s_lshl_b64 s[10:11], s[4:5], 11
	s_add_u32 s12, s78, s10
	s_addc_u32 s13, s79, s11
	v_lshl_add_u64 v[6:7], s[12:13], 0, v[24:25]
	v_lshl_add_u64 v[8:9], s[12:13], 0, v[26:27]
	s_or_b32 s12, s6, 0x80
	s_ashr_i32 s13, s12, 31
	v_add_u32_e32 v151, 0, v22
	s_lshl_b64 s[12:13], s[12:13], 11
	v_readfirstlane_b32 s5, v151
	v_add_u32_e32 v153, 0x2000, v151
	s_add_u32 s12, s20, s12
	s_cbranch_vccnz .Lipf_s1
	global_load_lds_dwordx4 v[2:3], off
.Lipf_s1:
	s_mov_b32 m0, s5
	v_readfirstlane_b32 s5, v153
	s_addc_u32 s13, s21, s13
	s_cbranch_vccnz .Lipf_s2
	global_load_lds_dwordx4 v[6:7], off
.Lipf_s2:
	s_mov_b32 m0, s5
	v_lshl_add_u64 v[12:13], s[12:13], 0, v[24:25]
	v_readlane_b32 s5, v255, 8
	v_lshl_add_u64 v[10:11], s[12:13], 0, v[26:27]
	s_or_b32 s12, s4, 0x80
	v_add_u32_e32 v154, s5, v22
	s_ashr_i32 s13, s12, 31
	v_readfirstlane_b32 s5, v154
	v_add_u32_e32 v155, 0x2000, v154
	s_lshl_b64 s[12:13], s[12:13], 11
	s_cbranch_vccnz .Lipf_s3
	global_load_lds_dwordx4 v[8:9], off
.Lipf_s3:
	s_mov_b32 m0, s5
	v_readfirstlane_b32 s5, v155
	s_add_u32 s12, s78, s12
	v_add_u32_e32 v157, 0x4000, v151
	s_cbranch_vccnz .Lipf_s4
	global_load_lds_dwordx4 v[12:13], off
.Lipf_s4:
	s_mov_b32 m0, s5
	s_addc_u32 s13, s79, s13
	v_readfirstlane_b32 s5, v157
	v_add_u32_e32 v158, 0x6000, v151
	s_cbranch_vccnz .Lipf_s5
	global_load_lds_dwordx4 v[10:11], off
.Lipf_s5:
	v_lshl_add_u64 v[132:133], s[12:13], 0, v[24:25]
	s_mov_b32 m0, s5
	v_readfirstlane_b32 s5, v158
	s_cbranch_vccnz .Lipf_s6
	global_load_lds_dwordx4 v[132:133], off
.Lipf_s6:
	v_lshl_add_u64 v[134:135], s[12:13], 0, v[26:27]
	s_mov_b32 m0, s5
	v_ashrrev_i32_e32 v23, 8, v4
	s_cbranch_vccnz .Lipf_s7
	global_load_lds_dwordx4 v[134:135], off
.Lipf_s7:
	v_cmp_eq_u32_e32 vcc, 1, v23
	s_and_saveexec_b64 s[12:13], vcc
	s_cbranch_execz .LBB0_84
	s_barrier
.LBB0_84:
	s_or_b64 exec, exec, s[12:13]
	v_readlane_b32 s7, v255, 9
	s_mov_b64 s[26:27], 0x80
	v_lshl_add_u64 v[0:1], v[0:1], 0, s[26:27]
	v_add_u32_e32 v159, s7, v22
	v_add_u32_e32 v160, 0x2000, v159
	v_readfirstlane_b32 s5, v159
	s_mov_b32 m0, s5
	v_readfirstlane_b32 s5, v160
	v_add_u32_e32 v161, 0x8000, v151
	v_cmp_ne_u32_e64 vcc, s32, 0
	s_cbranch_vccnz .Lipf_w4h
	s_waitcnt vmcnt(4)
	s_branch .Lipf_w4d
.Lipf_w4h:
	s_waitcnt vmcnt(63)
; #define G8_WV(n) asm volatile("s_waitcnt vmcnt(" #n ")" ::: "memory")
; #define G8_BAR __builtin_amdgcn_s_barrier()
; DI void gemm8p(const u16* __restrict__ A, const u16* __restrict__ Bt, int brow, int bcol, f32x4 (&acc)[2][2][4][2]) {
;     ...
;   const int wid = tid8 >> 6, lane = tid8 & 63, wr = wid >> 2, wc = wid & 3, fr = lane & 15, fq = lane >> 4;
;   int soff0, soff1;
;   { int r_, c_; g8_stage_rc(tid8 * 16, r_, c_); soff0 = r_ * K + c_; g8_stage_rc(tid8 * 16 + 8192, r_, c_); soff1 = r_ * K + c_; }
;   bf16x8 At[4][2], B0[2][2], B1[2][2];
;   constexpr int nt = K / BK;
;   __syncthreads();
;   G8_STAGE(G8_SB(0, 0), Bt, bcol, 0); G8_STAGE(G8_SA(0, 0), A, brow, 0);
;   G8_STAGE(G8_SB(0, 1), Bt, bcol + HALF, 0); G8_STAGE(G8_SA(0, 1), A, brow + HALF, 0);
;   if (wr == 1) G8_BAR;
;   G8_WV(4); G8_BAR;
;   G8_STAGE(G8_SB(1, 0), Bt, bcol, 1); G8_STAGE(G8_SA(1, 0), A, brow, 1); G8_STAGE(G8_SB(1, 1), Bt, bcol + HALF, 1);
;   G8_WV(6); G8_BAR;
; DI void phase_inproj(const Params& p, int layer, char* lds) {
;     ...
; #pragma unroll
;     for (int ai = 0; ai < 2; ++ai)
; #pragma unroll
;       for (int bj = 0; bj < 2; ++bj)
; #pragma unroll
;         for (int m = 0; m < 4; ++m)
; #pragma unroll
;           for (int n = 0; n < 2; ++n) acc[ai][bj][m][n] = (f32x4){0.f, 0.f, 0.f, 0.f};
.Lipf_w4d:
	s_barrier
	global_load_lds_dwordx4 v[0:1], off
	v_lshl_add_u64 v[0:1], v[2:3], 0, s[26:27]
	s_mov_b32 m0, s5
	v_readfirstlane_b32 s5, v161
	v_add_u32_e32 v162, 0xa000, v151
	v_readlane_b32 s12, v255, 10
	global_load_lds_dwordx4 v[0:1], off
	v_lshl_add_u64 v[0:1], v[6:7], 0, s[26:27]
	s_mov_b32 m0, s5
	v_readfirstlane_b32 s5, v162
	v_add_u32_e32 v163, s12, v22
	global_load_lds_dwordx4 v[0:1], off
	v_lshl_add_u64 v[0:1], v[8:9], 0, s[26:27]
	s_mov_b32 m0, s5
	v_readfirstlane_b32 s5, v163
	v_add_u32_e32 v164, 0x2000, v163
	global_load_lds_dwordx4 v[0:1], off
	v_lshl_add_u64 v[0:1], v[12:13], 0, s[26:27]
	s_mov_b32 m0, s5
	v_readfirstlane_b32 s5, v164
	global_load_lds_dwordx4 v[0:1], off
	v_lshl_add_u64 v[0:1], v[10:11], 0, s[26:27]
	s_mov_b32 m0, s5
	v_and_b32_e32 v24, 15, v4
	global_load_lds_dwordx4 v[0:1], off
	v_lshlrev_b32_e32 v1, 2, v4
	v_and_b32_e32 v25, 48, v4
	v_lshlrev_b32_e32 v0, 6, v24
	v_and_b32_e32 v1, 32, v1
	v_bitop3_b32 v0, v0, v1, v25 bitop3:0x36
	v_readlane_b32 s5, v255, 7
	v_lshlrev_b32_e32 v2, 6, v4
	v_add_u32_e32 v8, s7, v0
	v_add_u32_e32 v6, s5, v0
	v_readlane_b32 s5, v255, 8
	v_add_u32_e32 v9, s12, v0
	v_add_u32_e32 v12, 0, v0
	v_add_u32_e32 v7, s5, v0
	s_movk_i32 s5, 0x3c0
	v_and_or_b32 v0, v2, s5, v25
	v_xad_u32 v13, v0, v1, 0
	v_lshlrev_b32_e32 v0, 13, v14
	v_and_b32_e32 v10, 0x3000, v2
	v_and_b32_e32 v0, 0xffffc000, v0
	v_lshlrev_b32_e32 v2, 13, v18
	v_lshl_add_u32 v0, v15, 10, v0
	v_and_b32_e32 v2, 0xffffc000, v2
	v_or_b32_e32 v0, v0, v16
	v_lshl_add_u32 v2, v19, 10, v2
	v_readlane_b32 s12, v255, 20
	v_add_u32_sdwa v0, v0, sext(v17) dst_sel:DWORD dst_unused:UNUSED_PAD src0_sel:DWORD src1_sel:WORD_0
	v_or_b32_e32 v2, v2, v20
	v_readlane_b32 s13, v255, 21
	s_add_u32 s8, s12, s8
	v_ashrrev_i32_e32 v1, 31, v0
	v_add_u32_sdwa v2, v2, sext(v21) dst_sel:DWORD dst_unused:UNUSED_PAD src0_sel:DWORD src1_sel:WORD_0
	v_cmp_ne_u32_e64 vcc, s32, 0
	s_cbranch_vccnz .Lipf_w6
	s_waitcnt vmcnt(6)
.Lipf_w6:
	v_lshlrev_b32_e32 v11, 13, v23
	s_addc_u32 s9, s13, s9
	v_lshlrev_b64 v[0:1], 1, v[0:1]
	v_ashrrev_i32_e32 v3, 31, v2
	v_or_b32_e32 v22, 0x800, v11
	v_or_b32_e32 v23, 0x1000, v11
	v_or_b32_e32 v24, 0x1800, v11
	v_lshl_add_u64 v[136:137], s[8:9], 0, v[0:1]
	v_lshlrev_b64 v[2:3], 1, v[2:3]
	v_lshl_add_u64 v[140:141], s[10:11], 0, v[0:1]
	v_mov_b32_e32 v0, 0
	v_lshl_add_u64 v[138:139], s[8:9], 0, v[2:3]
	v_lshl_add_u64 v[142:143], s[10:11], 0, v[2:3]
	s_mov_b32 s5, -2
	v_add_u32_e32 v166, v6, v10
	v_add_u32_e32 v148, v12, v11
	v_add_u32_e32 v147, v13, v22
	v_add_u32_e32 v146, v13, v23
	v_add_u32_e32 v145, v13, v24
	v_add_u32_e32 v165, v7, v10
	v_add_u32_e32 v156, v8, v10
	v_add_u32_e32 v152, v9, v10
	v_mov_b32_e32 v1, v0
	v_mov_b32_e32 v2, v0
	v_mov_b32_e32 v3, v0
	v_mov_b32_e32 v6, v0
	v_mov_b32_e32 v7, v0
	v_mov_b32_e32 v8, v0
	v_mov_b32_e32 v9, v0
	v_mov_b32_e32 v10, v0
	v_mov_b32_e32 v11, v0
	v_mov_b32_e32 v12, v0
	v_mov_b32_e32 v13, v0
	v_mov_b32_e32 v14, v0
	v_mov_b32_e32 v15, v0
	v_mov_b32_e32 v16, v0
	v_mov_b32_e32 v17, v0
	v_mov_b32_e32 v18, v0
	v_mov_b32_e32 v19, v0
	v_mov_b32_e32 v20, v0
	v_mov_b32_e32 v21, v0
	v_mov_b32_e32 v22, v0
	v_mov_b32_e32 v23, v0
	v_mov_b32_e32 v24, v0
	v_mov_b32_e32 v25, v0
	v_mov_b32_e32 v26, v0
	v_mov_b32_e32 v27, v0
	v_mov_b32_e32 v28, v0
	v_mov_b32_e32 v29, v0
	v_mov_b32_e32 v30, v0
	v_mov_b32_e32 v31, v0
	v_mov_b32_e32 v32, v0
	v_mov_b32_e32 v33, v0
	v_mov_b32_e32 v34, v0
	v_mov_b32_e32 v35, v0
	v_mov_b32_e32 v36, v0
	v_mov_b32_e32 v37, v0
	v_mov_b32_e32 v38, v0
	v_mov_b32_e32 v39, v0
	v_mov_b32_e32 v40, v0
	v_mov_b32_e32 v41, v0
	v_mov_b32_e32 v42, v0
	v_mov_b32_e32 v43, v0
	v_mov_b32_e32 v44, v0
	v_mov_b32_e32 v45, v0
	v_mov_b32_e32 v46, v0
	v_mov_b32_e32 v47, v0
	v_mov_b32_e32 v48, v0
	v_mov_b32_e32 v49, v0
	v_mov_b32_e32 v50, v0
	v_mov_b32_e32 v51, v0
	v_mov_b32_e32 v52, v0
	v_mov_b32_e32 v53, v0
	v_mov_b32_e32 v54, v0
	v_mov_b32_e32 v55, v0
	v_mov_b32_e32 v56, v0
	v_mov_b32_e32 v57, v0
	v_mov_b32_e32 v58, v0
	v_mov_b32_e32 v59, v0
	v_mov_b32_e32 v60, v0
	v_mov_b32_e32 v61, v0
	v_mov_b32_e32 v62, v0
	v_mov_b32_e32 v63, v0
	v_mov_b32_e32 v64, v0
	v_mov_b32_e32 v65, v0
	v_mov_b32_e32 v66, v0
	v_mov_b32_e32 v67, v0
	v_mov_b32_e32 v68, v0
	v_mov_b32_e32 v69, v0
	v_mov_b32_e32 v70, v0
	v_mov_b32_e32 v71, v0
	v_mov_b32_e32 v72, v0
	v_mov_b32_e32 v73, v0
	v_mov_b32_e32 v74, v0
	v_mov_b32_e32 v75, v0
	v_mov_b32_e32 v76, v0
	v_mov_b32_e32 v77, v0
	v_mov_b32_e32 v78, v0
	v_mov_b32_e32 v79, v0
	v_mov_b32_e32 v80, v0
	v_mov_b32_e32 v81, v0
	v_mov_b32_e32 v82, v0
	v_mov_b32_e32 v83, v0
	v_mov_b32_e32 v84, v0
	v_mov_b32_e32 v85, v0
	v_mov_b32_e32 v86, v0
	v_mov_b32_e32 v87, v0
	v_mov_b32_e32 v88, v0
	v_mov_b32_e32 v89, v0
	v_mov_b32_e32 v90, v0
	v_mov_b32_e32 v91, v0
	v_mov_b32_e32 v92, v0
	v_mov_b32_e32 v93, v0
	v_mov_b32_e32 v94, v0
	v_mov_b32_e32 v95, v0
	v_mov_b32_e32 v96, v0
	v_mov_b32_e32 v97, v0
	v_mov_b32_e32 v98, v0
	v_mov_b32_e32 v99, v0
	v_mov_b32_e32 v100, v0
	v_mov_b32_e32 v101, v0
	v_mov_b32_e32 v102, v0
	v_mov_b32_e32 v103, v0
	v_mov_b32_e32 v104, v0
	v_mov_b32_e32 v105, v0
	v_mov_b32_e32 v106, v0
	v_mov_b32_e32 v107, v0
	v_mov_b32_e32 v108, v0
	v_mov_b32_e32 v109, v0
	v_mov_b32_e32 v110, v0
	v_mov_b32_e32 v111, v0
	v_mov_b32_e32 v112, v0
	v_mov_b32_e32 v113, v0
	v_mov_b32_e32 v114, v0
	v_mov_b32_e32 v115, v0
	v_mov_b32_e32 v116, v0
	v_mov_b32_e32 v117, v0
	v_mov_b32_e32 v118, v0
	v_mov_b32_e32 v119, v0
	v_mov_b32_e32 v120, v0
	v_mov_b32_e32 v121, v0
	v_mov_b32_e32 v122, v0
	v_mov_b32_e32 v123, v0
	v_mov_b32_e32 v124, v0
	v_mov_b32_e32 v125, v0
	v_mov_b32_e32 v126, v0
	v_mov_b32_e32 v127, v0
	v_mov_b32_e32 v128, v0
	v_mov_b32_e32 v129, v0
	s_barrier

; DI u16 f2bf(float x) { unsigned u = __float_as_uint(x); u += 0x7fffu + ((u >> 16) & 1u); return (u16)(u >> 16); }
; DI void phase_inproj(const Params& p, int layer, char* lds) {
;     ...
;   for (int u = bl; u < per_x; u += nbl) {
;     const int lr = u / NTN, nt = u % NTN;
;     const int mt = xcd_ok ? lr * 8 + xj : lr, m0 = mt * 256, n0 = nt * 256;
;     const int nvalid = (DIN - n0) < 256 ? (DIN - n0) : 256;
;     ...
;     const int wr8 = w >> 2, wc8 = w & 3, fr = lane & 15, fq = lane >> 4;
; #pragma unroll
;     for (int bj = 0; bj < 2; ++bj)
; #pragma unroll
;       for (int n = 0; n < 2; ++n) {
;         const int cw = n0 + bj * 128 + wc8 * 32 + n * 16, col = cw + fr;
;         u16* dst = H + cw; int dstr = DIN;
;         {
;           const int bb = m0 / S;
;           if (cw >= C_DK && cw < C_DV) { const int o = cw - C_DK; dst = (u16*)(p.ws + OFF_DK) + ((size_t)(bb * 3 * S + (o >> 6) * S) << 6) + (o & 63); dstr = 64; }
;           else if (cw >= C_DV && cw < C_SQ) { const int o = cw - C_DV; dst = (u16*)(p.ws + OFF_DV) + ((size_t)(bb * 3 * S + (o >> 6) * S) << 6) + (o & 63); dstr = 64; }
;           else if (cw >= C_SK && cw < C_SV) { const int o = cw - C_SK; dst = (u16*)(p.ws + OFF_SK) + ((size_t)(bb * 1 * S + (o >> 6) * S) << 6) + (o & 63); dstr = 64; }
;           else if (cw >= C_SV && cw < C_GATE) { const int o = cw - C_SV; dst = (u16*)(p.ws + OFF_SV) + ((size_t)(bb * 1 * S + (o >> 6) * S) << 6) + (o & 63); dstr = 64; }
;         }
;         if (cw < DIN) {
;           float sc = 1.f;
;           if (col >= C_DQ && col < C_DK) sc = SC_DQ;
;           if (col >= C_SQ && col < C_SK) sc = SC_SQ;
;           const bool gate = col >= C_GATE;
; #pragma unroll
;           for (int ai = 0; ai < 2; ++ai)
; #pragma unroll
;             for (int m = 0; m < 4; ++m) {
; #pragma unroll
;               for (int j = 0; j < 4; ++j) {
;                 const int row = m0 + ai * 128 + wr8 * 64 + m * 16 + fq * 4 + j;
;                 float v = acc[ai][bj][m][n][j] * sc;
;                 if (gate) v = v * __builtin_amdgcn_rcpf(1.f + __expf(-v));
;                 dst[(size_t)row * dstr + fr] = f2bf(v);
;               }
;               __builtin_amdgcn_sched_barrier(0);
;             }
.LBB0_88:
	s_or_b64 exec, exec, s[8:9]
	s_mov_b32 s32, 0
	s_add_i32 s7, s23, s63
	v_readlane_b32 s12, v254, 32
	v_lshlrev_b32_e32 v150, 4, v184
	s_cmp_lt_i32 s7, s12
	s_cbranch_scc0 .Lipf_none
	s_mov_b32 s32, 1
	s_mul_hi_i32 s12, s7, 0x2e8ba2e9
	s_lshr_b32 s13, s12, 31
	s_ashr_i32 s12, s12, 1
	s_add_i32 s12, s12, s13
	s_mul_i32 s13, s12, 11
	s_sub_i32 s13, s7, s13
	s_lshl_b32 s13, s13, 19
	s_lshl_b32 s24, s12, 3
	s_or_b32 s24, s24, s28
	v_readlane_b32 s10, v254, 30
	v_readlane_b32 s11, v254, 31
	v_lshrrev_b32_e32 v151, 10, v150
	v_and_b32_e32 v152, 0x3ff, v150
	s_and_b64 s[10:11], s[10:11], exec
	s_cselect_b32 s24, s24, s12
	s_lshl_b32 s24, s24, 19
	s_add_u32 s10, s20, s13
	s_addc_u32 s11, s21, 0
	s_add_u32 s12, s78, s24
	s_addc_u32 s13, s79, 0
	v_lshrrev_b32_e32 v153, 4, v152
	v_and_b32_e32 v153, 32, v153
	v_xor_b32_e32 v152, v152, v153
	v_lshrrev_b32_e32 v153, 1, v151
	v_lshlrev_b32_e32 v153, 4, v153
	v_lshrrev_b32_e32 v154, 6, v152
	v_add_u32_e32 v153, v153, v154
	v_and_b32_e32 v154, 1, v151
	v_lshlrev_b32_e32 v154, 5, v154
	v_bfe_u32 v155, v152, 1, 5
	v_add_u32_e32 v154, v154, v155
	v_lshl_add_u32 v153, v153, 10, v154
	v_lshlrev_b32_e32 v156, 1, v153
	v_mov_b32_e32 v157, 0
	v_add_u32_e32 v158, 0x20000, v156
	v_mov_b32_e32 v159, 0
	v_readfirstlane_b32 s25, v150
	v_readlane_b32 s26, v255, 7
	v_readlane_b32 s27, v255, 8
	v_lshl_add_u64 v[160:161], s[10:11], 0, v[156:157]
	v_lshl_add_u64 v[162:163], s[10:11], 0, v[158:159]
	v_lshl_add_u64 v[164:165], s[12:13], 0, v[156:157]
	v_lshl_add_u64 v[166:167], s[12:13], 0, v[158:159]
	s_add_u32 s10, s10, 0x40000
	s_addc_u32 s11, s11, 0
	s_add_u32 s12, s12, 0x40000
	s_addc_u32 s13, s13, 0
	v_lshl_add_u64 v[168:169], s[10:11], 0, v[156:157]
	v_lshl_add_u64 v[170:171], s[10:11], 0, v[158:159]
	v_lshl_add_u64 v[172:173], s[12:13], 0, v[156:157]
	v_lshl_add_u64 v[174:175], s[12:13], 0, v[158:159]
	s_add_u32 s7, s26, s25
	s_mov_b32 m0, s7
	s_nop 0
	global_load_lds_dwordx4 v[160:161], off
	s_add_u32 s7, s7, 0x2000
	s_mov_b32 m0, s7
	s_nop 0
	global_load_lds_dwordx4 v[162:163], off
	s_mov_b32 m0, s25
	s_nop 0
	global_load_lds_dwordx4 v[164:165], off
	s_add_u32 s7, s25, 0x2000
	s_mov_b32 m0, s7
	s_nop 0
	global_load_lds_dwordx4 v[166:167], off
	s_add_u32 s7, s27, s25
	s_mov_b32 m0, s7
	s_nop 0
	global_load_lds_dwordx4 v[168:169], off
	s_add_u32 s7, s7, 0x2000
	s_mov_b32 m0, s7
	s_nop 0
	global_load_lds_dwordx4 v[170:171], off
	s_add_u32 s7, s25, 0x4000
	s_mov_b32 m0, s7
	s_nop 0
	global_load_lds_dwordx4 v[172:173], off
	s_add_u32 s7, s25, 0x6000
	s_mov_b32 m0, s7
	s_nop 0
	global_load_lds_dwordx4 v[174:175], off
.Lipf_none:
	s_nop 7
	v_mov_b32_e32 v137, 0x15c0
	v_mul_u32_u24_e32 v132, v144, v137
	v_lshl_add_u32 v132, v130, 1, v132
	v_add_u32_e32 v133, 0x15c0, v132
	v_add_u32_e32 v134, 0x2b80, v132
	v_add_u32_e32 v135, 0x4140, v132
	v_lshlrev_b32_e32 v136, 7, v144
	v_lshl_add_u32 v136, v130, 1, v136
	v_readfirstlane_b32 s26, v131
	s_lshr_b32 s27, s4, 13
	s_add_u32 s25, s6, s26
	s_cmpk_ge_u32 s25, 2784
	s_cbranch_scc1 .Lipe0_done
	s_cmpk_ge_u32 s25, 1760
	s_cbranch_scc1 .Lipe0_gate
	s_cmpk_ge_u32 s25, 1632
	s_cbranch_scc1 .Lipe0_sv
	s_cmpk_ge_u32 s25, 1504
	s_cbranch_scc1 .Lipe0_sk
	s_cmpk_ge_u32 s25, 1120
	s_cbranch_scc1 .Lipe0_sq
	s_cmpk_ge_u32 s25, 864
	s_cbranch_scc1 .Lipe0_dv
	s_cmpk_ge_u32 s25, 608
	s_cbranch_scc1 .Lipe0_dk
	s_cmpk_ge_u32 s25, 352
	s_cbranch_scc1 .Lipe0_dq
	s_mul_i32 s10, s4, 0x15c0
	s_lshl_b32 s11, s25, 1
	s_add_u32 s10, s10, s11
	s_add_u32 s8, s50, s10
	s_addc_u32 s9, s51, 0
	v_cvt_pk_bf16_f32 v137, v126, v127
	global_store_short v132, v137, s[8:9]
	global_store_short_d16_hi v133, v137, s[8:9]
	v_cvt_pk_bf16_f32 v138, v128, v129
	global_store_short v134, v138, s[8:9]
	global_store_short_d16_hi v135, v138, s[8:9]
	v_cvt_pk_bf16_f32 v137, v122, v123
	v_add_u32_e32 v139, 0x15c00, v132
	v_add_u32_e32 v140, 0x15c00, v133
	global_store_short v139, v137, s[8:9]
	global_store_short_d16_hi v140, v137, s[8:9]
	v_cvt_pk_bf16_f32 v138, v124, v125
	v_add_u32_e32 v139, 0x15c00, v134
	v_add_u32_e32 v140, 0x15c00, v135
	global_store_short v139, v138, s[8:9]
	global_store_short_d16_hi v140, v138, s[8:9]
	v_cvt_pk_bf16_f32 v137, v118, v119
	v_add_u32_e32 v139, 0x2b800, v132
	v_add_u32_e32 v140, 0x2b800, v133
	global_store_short v139, v137, s[8:9]
	global_store_short_d16_hi v140, v137, s[8:9]
	v_cvt_pk_bf16_f32 v138, v120, v121
	v_add_u32_e32 v139, 0x2b800, v134
	v_add_u32_e32 v140, 0x2b800, v135
	global_store_short v139, v138, s[8:9]
	global_store_short_d16_hi v140, v138, s[8:9]
	v_cvt_pk_bf16_f32 v137, v114, v115
	v_add_u32_e32 v139, 0x41400, v132
	v_add_u32_e32 v140, 0x41400, v133
	global_store_short v139, v137, s[8:9]
	global_store_short_d16_hi v140, v137, s[8:9]
	v_cvt_pk_bf16_f32 v138, v116, v117
	v_add_u32_e32 v139, 0x41400, v134
	v_add_u32_e32 v140, 0x41400, v135
	global_store_short v139, v138, s[8:9]
	global_store_short_d16_hi v140, v138, s[8:9]
	v_cvt_pk_bf16_f32 v137, v110, v111
	v_add_u32_e32 v139, 0xae000, v132
	v_add_u32_e32 v140, 0xae000, v133
	global_store_short v139, v137, s[8:9]
	global_store_short_d16_hi v140, v137, s[8:9]
	v_cvt_pk_bf16_f32 v138, v112, v113
	v_add_u32_e32 v139, 0xae000, v134
	v_add_u32_e32 v140, 0xae000, v135
	global_store_short v139, v138, s[8:9]
	global_store_short_d16_hi v140, v138, s[8:9]
	v_cvt_pk_bf16_f32 v137, v106, v107
	v_add_u32_e32 v139, 0xc3c00, v132
	v_add_u32_e32 v140, 0xc3c00, v133
	global_store_short v139, v137, s[8:9]
	global_store_short_d16_hi v140, v137, s[8:9]
	v_cvt_pk_bf16_f32 v138, v108, v109
	v_add_u32_e32 v139, 0xc3c00, v134
	v_add_u32_e32 v140, 0xc3c00, v135
	global_store_short v139, v138, s[8:9]
	global_store_short_d16_hi v140, v138, s[8:9]
	v_cvt_pk_bf16_f32 v137, v102, v103
	v_add_u32_e32 v139, 0xd9800, v132
	v_add_u32_e32 v140, 0xd9800, v133
	global_store_short v139, v137, s[8:9]
	global_store_short_d16_hi v140, v137, s[8:9]
	v_cvt_pk_bf16_f32 v138, v104, v105
	v_add_u32_e32 v139, 0xd9800, v134
	v_add_u32_e32 v140, 0xd9800, v135
	global_store_short v139, v138, s[8:9]
	global_store_short_d16_hi v140, v138, s[8:9]
	v_cvt_pk_bf16_f32 v137, v98, v99
	v_add_u32_e32 v139, 0xef400, v132
	v_add_u32_e32 v140, 0xef400, v133
	global_store_short v139, v137, s[8:9]
	global_store_short_d16_hi v140, v137, s[8:9]
	v_cvt_pk_bf16_f32 v138, v100, v101
	v_add_u32_e32 v139, 0xef400, v134
	v_add_u32_e32 v140, 0xef400, v135
	global_store_short v139, v138, s[8:9]
	global_store_short_d16_hi v140, v138, s[8:9]
	s_branch .Lipe0_done
